# diff-attn vector section: pack/row-sum interleaved with the running-max dependency chain (first tile enters through a plain copy)
# baseline (speedup 1.0000x reference)
.Lda_entry:
	v_max3_f32 v148, v64, v65, v66
	v_max3_f32 v154, v72, v73, v74
	v_max3_f32 v155, v80, v81, v82
	v_max3_f32 v170, v88, v89, v90
	v_max3_f32 v148, v148, v67, v68
	v_max3_f32 v154, v154, v75, v76
	v_max3_f32 v155, v155, v83, v84
	v_max3_f32 v170, v170, v91, v92
	v_max3_f32 v148, v148, v69, v70
	v_max3_f32 v154, v154, v77, v78
	v_max3_f32 v155, v155, v85, v86
	v_max3_f32 v170, v170, v93, v94
	v_max_f32_e32 v148, v148, v71
	v_max_f32_e32 v154, v154, v79
	v_max_f32_e32 v155, v155, v87
	v_max_f32_e32 v170, v170, v95
	v_max3_f32 v154, v148, v154, v155
	v_max_f32_e32 v154, v154, v170
	v_mov_b32_e32 v155, v154
	s_cmpk_gt_i32 s26, 0x5e8
	s_cselect_b64 vcc, -1, 0
	v_permlane32_swap_b32_e32 v155, v154
	v_cndmask_b32_e32 v148, 0, v165, vcc
	v_max_f32_e32 v170, v154, v155
	v_add_f32_e32 v154, v148, v170
	v_add_f32_e32 v155, v149, v171
	v_cmp_gt_f32_e32 vcc, v154, v155
	s_mov_b32 s58, 0
	s_cbranch_vccz .LBB0_329
	v_max_f32_e32 v154, v154, v154
	v_max_f32_e32 v155, v149, v149
	v_max_f32_e32 v155, v155, v154
	v_sub_f32_e32 v149, v149, v155
	v_exp_f32_e32 v153, v149
	s_mov_b32 s58, 1
	v_mov_b32_e32 v149, v155
	v_mul_f32_e32 v167, v167, v153
	s_branch .LBB0_329
.LBB0_325:
	v_cvt_pk_bf16_f32 v124, v148, v154
	v_add_f32_e32 v214, v154, v148
	v_cvt_pk_bf16_f32 v125, v155, v170
	v_add_f32_e32 v250, v193, v192
	v_add_f32_e32 v214, v155, v214
	v_add_f32_e32 v251, v209, v208
	v_add_f32_e32 v215, v205, v204
	v_add_f32_e32 v214, v170, v214
	v_max3_f32 v148, v64, v65, v66
	v_cvt_pk_bf16_f32 v126, v196, v197
	v_max3_f32 v154, v72, v73, v74
	v_add_f32_e32 v250, v194, v250
	v_max3_f32 v155, v80, v81, v82
	v_add_f32_e32 v251, v220, v251
	v_max3_f32 v170, v88, v89, v90
	v_cvt_pk_bf16_f32 v127, v198, v199
	v_max3_f32 v148, v148, v67, v68
	v_add_f32_e32 v215, v206, v215
	v_max3_f32 v154, v154, v75, v76
	v_cvt_pk_bf16_f32 v116, v192, v193
	v_max3_f32 v155, v155, v83, v84
	v_add_f32_e32 v250, v195, v250
	v_max3_f32 v170, v170, v91, v92
	v_add_f32_e32 v251, v221, v251
	v_max3_f32 v148, v148, v69, v70
	v_cvt_pk_bf16_f32 v117, v194, v195
	v_max3_f32 v154, v154, v77, v78
	v_add_f32_e32 v215, v207, v215
	v_max3_f32 v155, v155, v85, v86
	v_cvt_pk_bf16_f32 v118, v200, v201
	v_max3_f32 v170, v170, v93, v94
	v_add_f32_e32 v250, v200, v250
	v_max_f32_e32 v148, v148, v71
	v_add_f32_e32 v251, v226, v251
	v_max_f32_e32 v154, v154, v79
	v_cvt_pk_bf16_f32 v119, v202, v203
	v_max_f32_e32 v155, v155, v87
	v_add_f32_e32 v214, v196, v214
	v_max_f32_e32 v170, v170, v95
	v_add_f32_e32 v215, v222, v215
	v_max3_f32 v154, v148, v154, v155
	v_cvt_pk_bf16_f32 v120, v204, v205
	v_add_f32_e32 v250, v201, v250
	v_add_f32_e32 v251, v227, v251
	v_cvt_pk_bf16_f32 v121, v206, v207
	v_max_f32_e32 v154, v154, v170
	v_add_f32_e32 v214, v197, v214
	v_add_f32_e32 v215, v223, v215
	v_cvt_pk_bf16_f32 v122, v222, v223
	v_add_f32_e32 v250, v202, v250
	v_mov_b32_e32 v155, v154
	s_cmpk_gt_i32 s26, 0x5e8
	s_cselect_b64 vcc, -1, 0
	v_add_f32_e32 v251, v228, v251
	v_cvt_pk_bf16_f32 v123, v224, v225
	v_permlane32_swap_b32_e32 v155, v154
	v_cndmask_b32_e32 v148, 0, v165, vcc
	v_add_f32_e32 v214, v198, v214
	v_add_f32_e32 v215, v224, v215
	v_cvt_pk_bf16_f32 v112, v208, v209
	v_add_f32_e32 v250, v203, v250
	v_max_f32_e32 v170, v154, v155
	v_add_f32_e32 v251, v229, v251
	v_cvt_pk_bf16_f32 v113, v220, v221
	v_add_f32_e32 v214, v199, v214
	v_add_f32_e32 v215, v225, v215
	v_add_f32_e32 v154, v148, v170
	v_add_f32_e32 v155, v149, v171
	v_cvt_pk_bf16_f32 v114, v226, v227
	v_cvt_pk_bf16_f32 v115, v228, v229
	v_add_f32_e32 v250, v250, v251
	v_add_f32_e32 v214, v214, v215
	v_cmp_gt_f32_e32 vcc, v154, v155
	v_add_f32_e32 v250, v250, v214
	v_add_f32_e32 v167, v167, v250
	s_mov_b32 s58, 0
	s_cbranch_vccz .LBB0_329
	v_max_f32_e32 v154, v154, v154
	v_max_f32_e32 v155, v149, v149
	v_max_f32_e32 v155, v155, v154
	v_sub_f32_e32 v149, v149, v155
	v_exp_f32_e32 v153, v149
	s_mov_b32 s58, 1
	v_mov_b32_e32 v149, v155
	v_mul_f32_e32 v167, v167, v153

.LBB0_340:
	s_nop 0
	s_nop 0
	s_nop 0
	s_nop 0
	s_nop 0
	s_nop 0
	s_nop 0
	s_nop 0
	s_nop 0
	s_nop 0
	s_nop 0
	s_nop 0
	s_nop 0
	s_nop 0
	s_cmp_lg_u32 s18, 0
	s_cbranch_scc1 .Lda_exit_b
	s_barrier
